# phase 5: blocks >= 256 do weight conversion before their GEMM tile (overlap L2-bound GEMM with HBM-bound conversion per CU)
# speedup vs baseline: 1.0109x; 1.0039x over previous
.LBB0_812:
	v_mov_b32_e32 v252, 0
	ds_read_b64 v[250:251], v252
	s_waitcnt lgkmcnt(0)
	v_lshlrev_b32_e32 v0, 3, v196
	v_lshrrev_b32_e32 v148, 3, v196
	v_and_b32_e32 v149, 56, v0
	s_bitcmp1_b32 s84, 8
	s_cbranch_scc1 .Lp5_wconv
.Lp5_gemm:
	s_bitcmp0_b32 s84, 8
	s_cbranch_scc1 .LBB0_815
	s_nop 0

.LBB0_822:
	s_bitcmp1_b32 s84, 8
	s_cbranch_scc1 .LBB0_845
